# hm3 loop setprio pairs removed; prologue2 mod-projection loop software-pipelined (4 weight loads in flight per wave, counted vmcnt)
# speedup vs baseline: 1.0040x; 1.0008x over previous
.LBB0_151:
	v_add_u32_e32 v2, s33, v22
	v_add_u32_e32 v7, 0x1000, v2
	v_add_u32_e32 v9, 0x1200, v2
	v_add_u32_e32 v11, 0x1400, v2
	v_add_u32_e32 v13, 0x1600, v2
	v_add_u32_e32 v29, 0x1800, v2
	v_add_u32_e32 v46, 0x1a00, v2
	v_add_u32_e32 v47, 0x1c00, v2
	v_add_u32_e32 v2, 0x1e00, v2
	v_ashrrev_i32_e32 v30, 11, v7
	v_ashrrev_i32_e32 v31, 11, v9
	v_ashrrev_i32_e32 v32, 11, v11
	v_ashrrev_i32_e32 v33, 11, v13
	v_ashrrev_i32_e32 v34, 11, v29
	v_ashrrev_i32_e32 v35, 11, v46
	v_ashrrev_i32_e32 v36, 11, v47
	v_ashrrev_i32_e32 v37, 11, v2
	v_add_u32_e32 v30, s31, v30
	v_add_u32_e32 v38, s31, v31
	v_add_u32_e32 v39, s31, v32
	v_add_u32_e32 v40, s31, v33
	v_add_u32_e32 v41, s31, v34
	v_add_u32_e32 v42, s31, v35
	v_add_u32_e32 v44, s31, v36
	v_add_u32_e32 v48, s31, v37
	v_mul_hi_i32_i24_e32 v31, 0x12000, v30
	v_mul_i32_i24_e32 v30, 0x12000, v30
	v_mul_hi_i32_i24_e32 v33, 0x12000, v38
	v_mul_i32_i24_e32 v32, 0x12000, v38
	v_mul_hi_i32_i24_e32 v35, 0x12000, v39
	v_mul_i32_i24_e32 v34, 0x12000, v39
	v_mul_hi_i32_i24_e32 v37, 0x12000, v40
	v_mul_i32_i24_e32 v36, 0x12000, v40
	v_mul_hi_i32_i24_e32 v39, 0x12000, v41
	v_mul_i32_i24_e32 v38, 0x12000, v41
	v_mul_hi_i32_i24_e32 v41, 0x12000, v42
	v_mul_i32_i24_e32 v40, 0x12000, v42
	v_mul_hi_i32_i24_e32 v43, 0x12000, v44
	v_mul_i32_i24_e32 v42, 0x12000, v44
	v_mul_hi_i32_i24_e32 v45, 0x12000, v48
	v_mul_i32_i24_e32 v44, 0x12000, v48
	v_lshl_add_u64 v[30:31], v[14:15], 0, v[30:31]
	v_lshl_add_u64 v[32:33], v[16:17], 0, v[32:33]
	v_lshl_add_u64 v[34:35], v[18:19], 0, v[34:35]
	v_lshl_add_u64 v[36:37], v[20:21], 0, v[36:37]
	v_lshl_add_u64 v[38:39], v[14:15], 0, v[38:39]
	v_lshl_add_u64 v[40:41], v[16:17], 0, v[40:41]
	v_lshl_add_u64 v[42:43], v[18:19], 0, v[42:43]
	v_lshl_add_u64 v[44:45], v[20:21], 0, v[44:45]
	global_load_dword v48, v[30:31], off
	global_load_dword v49, v[32:33], off
	global_load_dword v50, v[34:35], off
	global_load_dword v51, v[36:37], off
	global_load_dword v52, v[38:39], off
	global_load_dword v53, v[40:41], off
	global_load_dword v54, v[42:43], off
	global_load_dword v55, v[44:45], off
	v_lshrrev_b32_e32 v7, 8, v7
	s_addk_i32 s33, 0x1000
	v_lshrrev_b32_e32 v29, 8, v29
	v_and_or_b32 v7, v7, s23, v1
	s_cmpk_lt_u32 s33, 0x2000
	v_lshrrev_b32_e32 v9, 8, v9
	v_lshrrev_b32_e32 v11, 8, v11
	v_lshrrev_b32_e32 v13, 8, v13
	v_lshrrev_b32_e32 v30, 8, v46
	v_lshrrev_b32_e32 v31, 8, v47
	v_lshrrev_b32_e32 v2, 8, v2
	v_and_or_b32 v29, v29, s23, v1
	v_mad_i32_i24 v7, v7, s16, v23
	v_mad_i32_i24 v9, v9, s16, v23
	v_mad_i32_i24 v11, v11, s16, v23
	v_mad_i32_i24 v13, v13, s16, v23
	v_mad_i32_i24 v30, v30, s16, v23
	v_mad_i32_i24 v31, v31, s16, v23
	v_mad_i32_i24 v2, v2, s16, v23
	v_mad_i32_i24 v29, v29, s16, v23
	s_waitcnt vmcnt(7)
	ds_write_b32 v7, v48
	s_waitcnt vmcnt(6)
	ds_write_b32 v9, v49
	s_waitcnt vmcnt(5)
	ds_write_b32 v11, v50
	s_waitcnt vmcnt(4)
	ds_write_b32 v13, v51
	s_waitcnt vmcnt(3)
	ds_write_b32 v29, v52
	s_waitcnt vmcnt(2)
	ds_write_b32 v30, v53
	s_waitcnt vmcnt(1)
	ds_write_b32 v31, v54
	s_waitcnt vmcnt(0)
	ds_write_b32 v2, v55
	s_cbranch_scc1 .LBB0_151
	s_add_i32 s33, s6, 0xffffd500
	s_cmpk_lt_u32 s33, 0x4000
	s_cselect_b64 s[34:35], -1, 0
	s_and_b64 s[36:37], s[34:35], exec
	s_cselect_b32 s38, 0xffffd500, s24
	s_and_b64 s[36:37], s[12:13], exec
	s_cselect_b32 s36, s38, 0
	s_and_b64 s[10:11], s[10:11], exec
	s_cselect_b32 s10, 0xd100000, 0
	s_add_u32 s37, s14, s10
	s_addc_u32 s38, s15, 0
	v_add_u32_e32 v2, s6, v0
	s_and_b64 s[10:11], s[34:35], exec
	v_add_u32_e32 v7, s36, v2
	s_cselect_b32 s34, s25, 0x9080000
	s_and_b64 s[10:11], s[12:13], exec
	v_or_b32_e32 v9, v7, v24
	s_cselect_b32 s10, s34, 0
	v_lshlrev_b32_e32 v9, 2, v9
	v_bitop3_b32 v11, v7, s26, v24 bitop3:0xc8
	s_add_u32 s10, s37, s10
	v_and_or_b32 v9, v9, 16, v11
	v_or_b32_e32 v11, v11, v26
	v_lshlrev_b32_e32 v2, 7, v2
	s_addc_u32 s11, s38, 0
	v_ashrrev_i32_e32 v7, 3, v7
	v_and_b32_e32 v2, 0x4000, v2
	v_lshlrev_b32_e32 v11, 6, v11
	v_mov_b32_e32 v18, 0
	s_mov_b32 s33, 0
	v_and_b32_e32 v7, 0xffffffe0, v7
	v_lshrrev_b32_e32 v9, 3, v9
	v_and_b32_e32 v11, 0x3c0, v11
	v_lshl_add_u64 v[20:21], s[10:11], 0, v[2:3]
	v_mov_b32_e32 v13, v25
	v_mov_b32_e32 v29, v28
	s_mov_b32 s10, 0
	v_mov_b32_e32 v19, v18
	v_mov_b32_e32 v16, v18
	v_mov_b32_e32 v17, v18
	v_mov_b32_e32 v14, v18
	v_mov_b32_e32 v15, v18
	v_mov_b32_e32 v219, 0
	v_add_u32_e32 v218, 0, v13
	v_lshrrev_b32_e32 v218, 6, v218
	v_or_b32_e32 v216, v218, v7
	v_mov_b32_e32 v218, v9
	v_ashrrev_i32_e32 v217, 31, v216
	v_or_b32_e32 v220, 0, v11
	v_lshlrev_b32_e32 v218, 10, v218
	v_lshlrev_b64 v[216:217], 15, v[216:217]
	v_bitop3_b32 v218, v220, v218, v27 bitop3:0xde
	v_lshl_add_u64 v[216:217], v[20:21], 0, v[216:217]
	v_lshl_add_u64 v[216:217], v[216:217], 0, v[218:219]
	global_load_dwordx4 v[200:203], v[216:217], off
	v_add_u32_e32 v218, 8, v13
	v_lshrrev_b32_e32 v218, 6, v218
	v_or_b32_e32 v216, v218, v7
	v_mov_b32_e32 v218, v9
	v_ashrrev_i32_e32 v217, 31, v216
	v_or_b32_e32 v220, 16, v11
	v_lshlrev_b32_e32 v218, 10, v218
	v_lshlrev_b64 v[216:217], 15, v[216:217]
	v_bitop3_b32 v218, v220, v218, v27 bitop3:0xde
	v_lshl_add_u64 v[216:217], v[20:21], 0, v[216:217]
	v_lshl_add_u64 v[216:217], v[216:217], 0, v[218:219]
	global_load_dwordx4 v[204:207], v[216:217], off
	v_add_u32_e32 v218, 16, v13
	v_lshrrev_b32_e32 v218, 6, v218
	v_or_b32_e32 v216, v218, v7
	v_mov_b32_e32 v218, v9
	v_ashrrev_i32_e32 v217, 31, v216
	v_or_b32_e32 v220, 32, v11
	v_lshlrev_b32_e32 v218, 10, v218
	v_lshlrev_b64 v[216:217], 15, v[216:217]
	v_bitop3_b32 v218, v220, v218, v27 bitop3:0xde
	v_lshl_add_u64 v[216:217], v[20:21], 0, v[216:217]
	v_lshl_add_u64 v[216:217], v[216:217], 0, v[218:219]
	global_load_dwordx4 v[208:211], v[216:217], off
	v_add_u32_e32 v218, 24, v13
	v_lshrrev_b32_e32 v218, 6, v218
	v_or_b32_e32 v216, v218, v7
	v_mov_b32_e32 v218, v9
	v_ashrrev_i32_e32 v217, 31, v216
	v_or_b32_e32 v220, 48, v11
	v_lshlrev_b32_e32 v218, 10, v218
	v_lshlrev_b64 v[216:217], 15, v[216:217]
	v_bitop3_b32 v218, v220, v218, v27 bitop3:0xde
	v_lshl_add_u64 v[216:217], v[20:21], 0, v[216:217]
	v_lshl_add_u64 v[216:217], v[216:217], 0, v[218:219]
	global_load_dwordx4 v[212:215], v[216:217], off
	s_waitcnt lgkmcnt(0)
	s_barrier
.Lp2_loop:
	ds_read_b128 v[30:33], v29
	ds_read_b128 v[34:37], v29 offset:16
	ds_read_b128 v[38:41], v29 offset:8320
	ds_read_b128 v[42:45], v29 offset:8336
	ds_read_b128 v[46:49], v29 offset:16640
	ds_read_b128 v[50:53], v29 offset:16656
	ds_read_b128 v[54:57], v29 offset:24960
	ds_read_b128 v[58:61], v29 offset:24976
	ds_read_b128 v[62:65], v29 offset:33280
	ds_read_b128 v[66:69], v29 offset:33296
	ds_read_b128 v[70:73], v29 offset:41600
	ds_read_b128 v[74:77], v29 offset:41616
	v_add_u32_e32 v218, 32, v13
	v_lshrrev_b32_e32 v218, 6, v218
	s_add_i32 s11, s10, 4
	s_lshr_b32 s11, s11, 2
	v_or_b32_e32 v216, v218, v7
	v_and_or_b32 v218, s11, 1, v9
	v_ashrrev_i32_e32 v217, 31, v216
	v_and_or_b32 v220, s33, 48, v11
	v_lshlrev_b32_e32 v218, 10, v218
	v_lshlrev_b64 v[216:217], 15, v[216:217]
	v_bitop3_b32 v218, v220, v218, v27 bitop3:0xde
	v_lshl_add_u64 v[216:217], v[20:21], 0, v[216:217]
	v_lshl_add_u64 v[216:217], v[216:217], 0, v[218:219]
	s_add_i32 s10, s10, 1
	s_add_i32 s33, s33, 16
	s_waitcnt lgkmcnt(1)
	v_mov_b32_e32 v82, v71
	v_mov_b32_e32 v83, v72
	v_mov_b32_e32 v71, v73
	v_mov_b32_e32 v72, v30
	v_mov_b32_e32 v73, v38
	v_mov_b32_e32 v38, v31
	v_mov_b32_e32 v30, v32
	v_mov_b32_e32 v31, v40
	v_mov_b32_e32 v40, v33
	v_mov_b32_e32 v32, v34
	v_mov_b32_e32 v33, v42
	v_mov_b32_e32 v42, v35
	v_mov_b32_e32 v34, v36
	v_mov_b32_e32 v35, v44
	v_mov_b32_e32 v44, v37
	v_mov_b32_e32 v36, v46
	v_mov_b32_e32 v37, v54
	v_mov_b32_e32 v54, v47
	v_mov_b32_e32 v46, v48
	v_mov_b32_e32 v47, v56
	v_mov_b32_e32 v56, v49
	v_mov_b32_e32 v48, v50
	v_mov_b32_e32 v49, v58
	v_mov_b32_e32 v58, v51
	v_mov_b32_e32 v50, v52
	v_mov_b32_e32 v51, v60
	v_mov_b32_e32 v60, v53
	s_waitcnt lgkmcnt(0)
	v_mov_b32_e32 v52, v74
	v_mov_b32_e32 v53, v76
	v_mov_b32_e32 v76, v75
	v_add_u32_e32 v29, 32, v29
	v_add_u32_e32 v13, 8, v13
	s_waitcnt vmcnt(3)
	v_and_b32_e32 v74, 0xffff0000, v200
	v_lshlrev_b32_e32 v75, 16, v201
	v_lshlrev_b32_e32 v78, 16, v200
	v_and_b32_e32 v79, 0xffff0000, v201
	v_lshlrev_b32_e32 v85, 16, v203
	v_lshlrev_b32_e32 v84, 16, v202
	v_and_b32_e32 v81, 0xffff0000, v203
	v_and_b32_e32 v80, 0xffff0000, v202
	global_load_dwordx4 v[200:203], v[216:217], off
	v_mov_b32_e32 v86, v78
	v_mov_b32_e32 v87, v74
	v_mul_f32_e32 v2, v63, v74
	v_mov_b32_e32 v88, v75
	v_mov_b32_e32 v89, v79
	v_mul_f32_e32 v90, v65, v79
	v_pk_mul_f32 v[70:71], v[70:71], v[78:79]
	v_pk_mul_f32 v[38:39], v[38:39], v[74:75] op_sel_hi:[1,0]
	v_pk_mul_f32 v[40:41], v[40:41], v[78:79] op_sel:[0,1]
	v_pk_mul_f32 v[54:55], v[54:55], v[74:75] op_sel_hi:[1,0]
	v_pk_mul_f32 v[56:57], v[56:57], v[78:79] op_sel:[0,1]
	v_pk_mul_f32 v[42:43], v[42:43], v[80:81] op_sel_hi:[1,0]
	v_mov_b32_e32 v92, v85
	v_pk_mul_f32 v[44:45], v[44:45], v[80:81] op_sel:[0,1]
	v_pk_mul_f32 v[58:59], v[58:59], v[80:81] op_sel_hi:[1,0]
	v_pk_mul_f32 v[60:61], v[60:61], v[80:81] op_sel:[0,1]
	v_mov_b32_e32 v94, v84
	v_mov_b32_e32 v95, v80
	v_mul_f32_e32 v96, v67, v80
	v_pk_mul_f32 v[76:77], v[76:77], v[80:81]
	v_pk_fma_f32 v[62:63], v[62:63], v[86:87], v[2:3] op_sel_hi:[1,1,0]
	v_pk_fma_f32 v[64:65], v[64:65], v[88:89], v[90:91] op_sel_hi:[1,1,0]
	v_pk_fma_f32 v[70:71], v[82:83], v[74:75], v[70:71]
	v_pk_fma_f32 v[38:39], v[72:73], v[78:79], v[38:39] op_sel_hi:[1,0,1]
	v_pk_fma_f32 v[30:31], v[30:31], v[74:75], v[40:41] op_sel:[0,1,0]
	v_pk_fma_f32 v[36:37], v[36:37], v[78:79], v[54:55] op_sel_hi:[1,0,1]
	v_pk_fma_f32 v[40:41], v[46:47], v[74:75], v[56:57] op_sel:[0,1,0]
	v_mov_b32_e32 v98, v85
	v_mov_b32_e32 v99, v81
	v_mul_f32_e32 v100, v69, v81
	v_pk_fma_f32 v[32:33], v[32:33], v[84:85], v[42:43] op_sel_hi:[1,0,1]
	v_pk_fma_f32 v[34:35], v[34:35], v[92:93], v[44:45] op_sel_hi:[1,0,1]
	v_pk_fma_f32 v[42:43], v[48:49], v[84:85], v[58:59] op_sel_hi:[1,0,1]
	v_pk_fma_f32 v[44:45], v[50:51], v[92:93], v[60:61] op_sel_hi:[1,0,1]
	v_pk_fma_f32 v[46:47], v[66:67], v[94:95], v[96:97] op_sel_hi:[1,1,0]
	v_pk_fma_f32 v[50:51], v[52:53], v[84:85], v[76:77]
	v_pk_add_f32 v[30:31], v[38:39], v[30:31]
	v_pk_add_f32 v[36:37], v[36:37], v[40:41]
	v_mov_b32_e32 v63, v70
	v_mov_b32_e32 v65, v71
	v_pk_fma_f32 v[48:49], v[68:69], v[98:99], v[100:101] op_sel_hi:[1,1,0]
	v_mov_b32_e32 v47, v50
	v_pk_add_f32 v[30:31], v[30:31], v[32:33]
	v_pk_add_f32 v[32:33], v[36:37], v[42:43]
	v_pk_add_f32 v[36:37], v[62:63], v[64:65]
	v_mov_b32_e32 v49, v51
	v_pk_add_f32 v[30:31], v[34:35], v[30:31]
	v_pk_add_f32 v[34:35], v[36:37], v[46:47]
	v_pk_add_f32 v[32:33], v[44:45], v[32:33]
	v_pk_add_f32 v[18:19], v[18:19], v[30:31]
	v_pk_add_f32 v[30:31], v[48:49], v[34:35]
	v_pk_add_f32 v[16:17], v[16:17], v[32:33]
	v_pk_add_f32 v[14:15], v[14:15], v[30:31]
	ds_read_b128 v[30:33], v29
	ds_read_b128 v[34:37], v29 offset:16
	ds_read_b128 v[38:41], v29 offset:8320
	ds_read_b128 v[42:45], v29 offset:8336
	ds_read_b128 v[46:49], v29 offset:16640
	ds_read_b128 v[50:53], v29 offset:16656
	ds_read_b128 v[54:57], v29 offset:24960
	ds_read_b128 v[58:61], v29 offset:24976
	ds_read_b128 v[62:65], v29 offset:33280
	ds_read_b128 v[66:69], v29 offset:33296
	ds_read_b128 v[70:73], v29 offset:41600
	ds_read_b128 v[74:77], v29 offset:41616
	v_add_u32_e32 v218, 32, v13
	v_lshrrev_b32_e32 v218, 6, v218
	s_add_i32 s11, s10, 4
	s_lshr_b32 s11, s11, 2
	v_or_b32_e32 v216, v218, v7
	v_and_or_b32 v218, s11, 1, v9
	v_ashrrev_i32_e32 v217, 31, v216
	v_and_or_b32 v220, s33, 48, v11
	v_lshlrev_b32_e32 v218, 10, v218
	v_lshlrev_b64 v[216:217], 15, v[216:217]
	v_bitop3_b32 v218, v220, v218, v27 bitop3:0xde
	v_lshl_add_u64 v[216:217], v[20:21], 0, v[216:217]
	v_lshl_add_u64 v[216:217], v[216:217], 0, v[218:219]
	s_add_i32 s10, s10, 1
	s_add_i32 s33, s33, 16
	s_waitcnt lgkmcnt(1)
	v_mov_b32_e32 v82, v71
	v_mov_b32_e32 v83, v72
	v_mov_b32_e32 v71, v73
	v_mov_b32_e32 v72, v30
	v_mov_b32_e32 v73, v38
	v_mov_b32_e32 v38, v31
	v_mov_b32_e32 v30, v32
	v_mov_b32_e32 v31, v40
	v_mov_b32_e32 v40, v33
	v_mov_b32_e32 v32, v34
	v_mov_b32_e32 v33, v42
	v_mov_b32_e32 v42, v35
	v_mov_b32_e32 v34, v36
	v_mov_b32_e32 v35, v44
	v_mov_b32_e32 v44, v37
	v_mov_b32_e32 v36, v46
	v_mov_b32_e32 v37, v54
	v_mov_b32_e32 v54, v47
	v_mov_b32_e32 v46, v48
	v_mov_b32_e32 v47, v56
	v_mov_b32_e32 v56, v49
	v_mov_b32_e32 v48, v50
	v_mov_b32_e32 v49, v58
	v_mov_b32_e32 v58, v51
	v_mov_b32_e32 v50, v52
	v_mov_b32_e32 v51, v60
	v_mov_b32_e32 v60, v53
	s_waitcnt lgkmcnt(0)
	v_mov_b32_e32 v52, v74
	v_mov_b32_e32 v53, v76
	v_mov_b32_e32 v76, v75
	v_add_u32_e32 v29, 32, v29
	v_add_u32_e32 v13, 8, v13
	s_waitcnt vmcnt(3)
	v_and_b32_e32 v74, 0xffff0000, v204
	v_lshlrev_b32_e32 v75, 16, v205
	v_lshlrev_b32_e32 v78, 16, v204
	v_and_b32_e32 v79, 0xffff0000, v205
	v_lshlrev_b32_e32 v85, 16, v207
	v_lshlrev_b32_e32 v84, 16, v206
	v_and_b32_e32 v81, 0xffff0000, v207
	v_and_b32_e32 v80, 0xffff0000, v206
	global_load_dwordx4 v[204:207], v[216:217], off
	v_mov_b32_e32 v86, v78
	v_mov_b32_e32 v87, v74
	v_mul_f32_e32 v2, v63, v74
	v_mov_b32_e32 v88, v75
	v_mov_b32_e32 v89, v79
	v_mul_f32_e32 v90, v65, v79
	v_pk_mul_f32 v[70:71], v[70:71], v[78:79]
	v_pk_mul_f32 v[38:39], v[38:39], v[74:75] op_sel_hi:[1,0]
	v_pk_mul_f32 v[40:41], v[40:41], v[78:79] op_sel:[0,1]
	v_pk_mul_f32 v[54:55], v[54:55], v[74:75] op_sel_hi:[1,0]
	v_pk_mul_f32 v[56:57], v[56:57], v[78:79] op_sel:[0,1]
	v_pk_mul_f32 v[42:43], v[42:43], v[80:81] op_sel_hi:[1,0]
	v_mov_b32_e32 v92, v85
	v_pk_mul_f32 v[44:45], v[44:45], v[80:81] op_sel:[0,1]
	v_pk_mul_f32 v[58:59], v[58:59], v[80:81] op_sel_hi:[1,0]
	v_pk_mul_f32 v[60:61], v[60:61], v[80:81] op_sel:[0,1]
	v_mov_b32_e32 v94, v84
	v_mov_b32_e32 v95, v80
	v_mul_f32_e32 v96, v67, v80
	v_pk_mul_f32 v[76:77], v[76:77], v[80:81]
	v_pk_fma_f32 v[62:63], v[62:63], v[86:87], v[2:3] op_sel_hi:[1,1,0]
	v_pk_fma_f32 v[64:65], v[64:65], v[88:89], v[90:91] op_sel_hi:[1,1,0]
	v_pk_fma_f32 v[70:71], v[82:83], v[74:75], v[70:71]
	v_pk_fma_f32 v[38:39], v[72:73], v[78:79], v[38:39] op_sel_hi:[1,0,1]
	v_pk_fma_f32 v[30:31], v[30:31], v[74:75], v[40:41] op_sel:[0,1,0]
	v_pk_fma_f32 v[36:37], v[36:37], v[78:79], v[54:55] op_sel_hi:[1,0,1]
	v_pk_fma_f32 v[40:41], v[46:47], v[74:75], v[56:57] op_sel:[0,1,0]
	v_mov_b32_e32 v98, v85
	v_mov_b32_e32 v99, v81
	v_mul_f32_e32 v100, v69, v81
	v_pk_fma_f32 v[32:33], v[32:33], v[84:85], v[42:43] op_sel_hi:[1,0,1]
	v_pk_fma_f32 v[34:35], v[34:35], v[92:93], v[44:45] op_sel_hi:[1,0,1]
	v_pk_fma_f32 v[42:43], v[48:49], v[84:85], v[58:59] op_sel_hi:[1,0,1]
	v_pk_fma_f32 v[44:45], v[50:51], v[92:93], v[60:61] op_sel_hi:[1,0,1]
	v_pk_fma_f32 v[46:47], v[66:67], v[94:95], v[96:97] op_sel_hi:[1,1,0]
	v_pk_fma_f32 v[50:51], v[52:53], v[84:85], v[76:77]
	v_pk_add_f32 v[30:31], v[38:39], v[30:31]
	v_pk_add_f32 v[36:37], v[36:37], v[40:41]
	v_mov_b32_e32 v63, v70
	v_mov_b32_e32 v65, v71
	v_pk_fma_f32 v[48:49], v[68:69], v[98:99], v[100:101] op_sel_hi:[1,1,0]
	v_mov_b32_e32 v47, v50
	v_pk_add_f32 v[30:31], v[30:31], v[32:33]
	v_pk_add_f32 v[32:33], v[36:37], v[42:43]
	v_pk_add_f32 v[36:37], v[62:63], v[64:65]
	v_mov_b32_e32 v49, v51
	v_pk_add_f32 v[30:31], v[34:35], v[30:31]
	v_pk_add_f32 v[34:35], v[36:37], v[46:47]
	v_pk_add_f32 v[32:33], v[44:45], v[32:33]
	v_pk_add_f32 v[18:19], v[18:19], v[30:31]
	v_pk_add_f32 v[30:31], v[48:49], v[34:35]
	v_pk_add_f32 v[16:17], v[16:17], v[32:33]
	v_pk_add_f32 v[14:15], v[14:15], v[30:31]
	ds_read_b128 v[30:33], v29
	ds_read_b128 v[34:37], v29 offset:16
	ds_read_b128 v[38:41], v29 offset:8320
	ds_read_b128 v[42:45], v29 offset:8336
	ds_read_b128 v[46:49], v29 offset:16640
	ds_read_b128 v[50:53], v29 offset:16656
	ds_read_b128 v[54:57], v29 offset:24960
	ds_read_b128 v[58:61], v29 offset:24976
	ds_read_b128 v[62:65], v29 offset:33280
	ds_read_b128 v[66:69], v29 offset:33296
	ds_read_b128 v[70:73], v29 offset:41600
	ds_read_b128 v[74:77], v29 offset:41616
	v_add_u32_e32 v218, 32, v13
	v_lshrrev_b32_e32 v218, 6, v218
	s_add_i32 s11, s10, 4
	s_lshr_b32 s11, s11, 2
	v_or_b32_e32 v216, v218, v7
	v_and_or_b32 v218, s11, 1, v9
	v_ashrrev_i32_e32 v217, 31, v216
	v_and_or_b32 v220, s33, 48, v11
	v_lshlrev_b32_e32 v218, 10, v218
	v_lshlrev_b64 v[216:217], 15, v[216:217]
	v_bitop3_b32 v218, v220, v218, v27 bitop3:0xde
	v_lshl_add_u64 v[216:217], v[20:21], 0, v[216:217]
	v_lshl_add_u64 v[216:217], v[216:217], 0, v[218:219]
	s_add_i32 s10, s10, 1
	s_add_i32 s33, s33, 16
	s_waitcnt lgkmcnt(1)
	v_mov_b32_e32 v82, v71
	v_mov_b32_e32 v83, v72
	v_mov_b32_e32 v71, v73
	v_mov_b32_e32 v72, v30
	v_mov_b32_e32 v73, v38
	v_mov_b32_e32 v38, v31
	v_mov_b32_e32 v30, v32
	v_mov_b32_e32 v31, v40
	v_mov_b32_e32 v40, v33
	v_mov_b32_e32 v32, v34
	v_mov_b32_e32 v33, v42
	v_mov_b32_e32 v42, v35
	v_mov_b32_e32 v34, v36
	v_mov_b32_e32 v35, v44
	v_mov_b32_e32 v44, v37
	v_mov_b32_e32 v36, v46
	v_mov_b32_e32 v37, v54
	v_mov_b32_e32 v54, v47
	v_mov_b32_e32 v46, v48
	v_mov_b32_e32 v47, v56
	v_mov_b32_e32 v56, v49
	v_mov_b32_e32 v48, v50
	v_mov_b32_e32 v49, v58
	v_mov_b32_e32 v58, v51
	v_mov_b32_e32 v50, v52
	v_mov_b32_e32 v51, v60
	v_mov_b32_e32 v60, v53
	s_waitcnt lgkmcnt(0)
	v_mov_b32_e32 v52, v74
	v_mov_b32_e32 v53, v76
	v_mov_b32_e32 v76, v75
	v_add_u32_e32 v29, 32, v29
	v_add_u32_e32 v13, 8, v13
	s_waitcnt vmcnt(3)
	v_and_b32_e32 v74, 0xffff0000, v208
	v_lshlrev_b32_e32 v75, 16, v209
	v_lshlrev_b32_e32 v78, 16, v208
	v_and_b32_e32 v79, 0xffff0000, v209
	v_lshlrev_b32_e32 v85, 16, v211
	v_lshlrev_b32_e32 v84, 16, v210
	v_and_b32_e32 v81, 0xffff0000, v211
	v_and_b32_e32 v80, 0xffff0000, v210
	global_load_dwordx4 v[208:211], v[216:217], off
	v_mov_b32_e32 v86, v78
	v_mov_b32_e32 v87, v74
	v_mul_f32_e32 v2, v63, v74
	v_mov_b32_e32 v88, v75
	v_mov_b32_e32 v89, v79
	v_mul_f32_e32 v90, v65, v79
	v_pk_mul_f32 v[70:71], v[70:71], v[78:79]
	v_pk_mul_f32 v[38:39], v[38:39], v[74:75] op_sel_hi:[1,0]
	v_pk_mul_f32 v[40:41], v[40:41], v[78:79] op_sel:[0,1]
	v_pk_mul_f32 v[54:55], v[54:55], v[74:75] op_sel_hi:[1,0]
	v_pk_mul_f32 v[56:57], v[56:57], v[78:79] op_sel:[0,1]
	v_pk_mul_f32 v[42:43], v[42:43], v[80:81] op_sel_hi:[1,0]
	v_mov_b32_e32 v92, v85
	v_pk_mul_f32 v[44:45], v[44:45], v[80:81] op_sel:[0,1]
	v_pk_mul_f32 v[58:59], v[58:59], v[80:81] op_sel_hi:[1,0]
	v_pk_mul_f32 v[60:61], v[60:61], v[80:81] op_sel:[0,1]
	v_mov_b32_e32 v94, v84
	v_mov_b32_e32 v95, v80
	v_mul_f32_e32 v96, v67, v80
	v_pk_mul_f32 v[76:77], v[76:77], v[80:81]
	v_pk_fma_f32 v[62:63], v[62:63], v[86:87], v[2:3] op_sel_hi:[1,1,0]
	v_pk_fma_f32 v[64:65], v[64:65], v[88:89], v[90:91] op_sel_hi:[1,1,0]
	v_pk_fma_f32 v[70:71], v[82:83], v[74:75], v[70:71]
	v_pk_fma_f32 v[38:39], v[72:73], v[78:79], v[38:39] op_sel_hi:[1,0,1]
	v_pk_fma_f32 v[30:31], v[30:31], v[74:75], v[40:41] op_sel:[0,1,0]
	v_pk_fma_f32 v[36:37], v[36:37], v[78:79], v[54:55] op_sel_hi:[1,0,1]
	v_pk_fma_f32 v[40:41], v[46:47], v[74:75], v[56:57] op_sel:[0,1,0]
	v_mov_b32_e32 v98, v85
	v_mov_b32_e32 v99, v81
	v_mul_f32_e32 v100, v69, v81
	v_pk_fma_f32 v[32:33], v[32:33], v[84:85], v[42:43] op_sel_hi:[1,0,1]
	v_pk_fma_f32 v[34:35], v[34:35], v[92:93], v[44:45] op_sel_hi:[1,0,1]
	v_pk_fma_f32 v[42:43], v[48:49], v[84:85], v[58:59] op_sel_hi:[1,0,1]
	v_pk_fma_f32 v[44:45], v[50:51], v[92:93], v[60:61] op_sel_hi:[1,0,1]
	v_pk_fma_f32 v[46:47], v[66:67], v[94:95], v[96:97] op_sel_hi:[1,1,0]
	v_pk_fma_f32 v[50:51], v[52:53], v[84:85], v[76:77]
	v_pk_add_f32 v[30:31], v[38:39], v[30:31]
	v_pk_add_f32 v[36:37], v[36:37], v[40:41]
	v_mov_b32_e32 v63, v70
	v_mov_b32_e32 v65, v71
	v_pk_fma_f32 v[48:49], v[68:69], v[98:99], v[100:101] op_sel_hi:[1,1,0]
	v_mov_b32_e32 v47, v50
	v_pk_add_f32 v[30:31], v[30:31], v[32:33]
	v_pk_add_f32 v[32:33], v[36:37], v[42:43]
	v_pk_add_f32 v[36:37], v[62:63], v[64:65]
	v_mov_b32_e32 v49, v51
	v_pk_add_f32 v[30:31], v[34:35], v[30:31]
	v_pk_add_f32 v[34:35], v[36:37], v[46:47]
	v_pk_add_f32 v[32:33], v[44:45], v[32:33]
	v_pk_add_f32 v[18:19], v[18:19], v[30:31]
	v_pk_add_f32 v[30:31], v[48:49], v[34:35]
	v_pk_add_f32 v[16:17], v[16:17], v[32:33]
	v_pk_add_f32 v[14:15], v[14:15], v[30:31]
	ds_read_b128 v[30:33], v29
	ds_read_b128 v[34:37], v29 offset:16
	ds_read_b128 v[38:41], v29 offset:8320
	ds_read_b128 v[42:45], v29 offset:8336
	ds_read_b128 v[46:49], v29 offset:16640
	ds_read_b128 v[50:53], v29 offset:16656
	ds_read_b128 v[54:57], v29 offset:24960
	ds_read_b128 v[58:61], v29 offset:24976
	ds_read_b128 v[62:65], v29 offset:33280
	ds_read_b128 v[66:69], v29 offset:33296
	ds_read_b128 v[70:73], v29 offset:41600
	ds_read_b128 v[74:77], v29 offset:41616
	v_add_u32_e32 v218, 32, v13
	v_lshrrev_b32_e32 v218, 6, v218
	s_add_i32 s11, s10, 4
	s_lshr_b32 s11, s11, 2
	v_or_b32_e32 v216, v218, v7
	v_and_or_b32 v218, s11, 1, v9
	v_ashrrev_i32_e32 v217, 31, v216
	v_and_or_b32 v220, s33, 48, v11
	v_lshlrev_b32_e32 v218, 10, v218
	v_lshlrev_b64 v[216:217], 15, v[216:217]
	v_bitop3_b32 v218, v220, v218, v27 bitop3:0xde
	v_lshl_add_u64 v[216:217], v[20:21], 0, v[216:217]
	v_lshl_add_u64 v[216:217], v[216:217], 0, v[218:219]
	s_add_i32 s10, s10, 1
	s_add_i32 s33, s33, 16
	s_waitcnt lgkmcnt(1)
	v_mov_b32_e32 v82, v71
	v_mov_b32_e32 v83, v72
	v_mov_b32_e32 v71, v73
	v_mov_b32_e32 v72, v30
	v_mov_b32_e32 v73, v38
	v_mov_b32_e32 v38, v31
	v_mov_b32_e32 v30, v32
	v_mov_b32_e32 v31, v40
	v_mov_b32_e32 v40, v33
	v_mov_b32_e32 v32, v34
	v_mov_b32_e32 v33, v42
	v_mov_b32_e32 v42, v35
	v_mov_b32_e32 v34, v36
	v_mov_b32_e32 v35, v44
	v_mov_b32_e32 v44, v37
	v_mov_b32_e32 v36, v46
	v_mov_b32_e32 v37, v54
	v_mov_b32_e32 v54, v47
	v_mov_b32_e32 v46, v48
	v_mov_b32_e32 v47, v56
	v_mov_b32_e32 v56, v49
	v_mov_b32_e32 v48, v50
	v_mov_b32_e32 v49, v58
	v_mov_b32_e32 v58, v51
	v_mov_b32_e32 v50, v52
	v_mov_b32_e32 v51, v60
	v_mov_b32_e32 v60, v53
	s_waitcnt lgkmcnt(0)
	v_mov_b32_e32 v52, v74
	v_mov_b32_e32 v53, v76
	v_mov_b32_e32 v76, v75
	v_add_u32_e32 v29, 32, v29
	v_add_u32_e32 v13, 8, v13
	s_cmp_eq_u32 s10, 28
	s_waitcnt vmcnt(3)
	v_and_b32_e32 v74, 0xffff0000, v212
	v_lshlrev_b32_e32 v75, 16, v213
	v_lshlrev_b32_e32 v78, 16, v212
	v_and_b32_e32 v79, 0xffff0000, v213
	v_lshlrev_b32_e32 v85, 16, v215
	v_lshlrev_b32_e32 v84, 16, v214
	v_and_b32_e32 v81, 0xffff0000, v215
	v_and_b32_e32 v80, 0xffff0000, v214
	global_load_dwordx4 v[212:215], v[216:217], off
	v_mov_b32_e32 v86, v78
	v_mov_b32_e32 v87, v74
	v_mul_f32_e32 v2, v63, v74
	v_mov_b32_e32 v88, v75
	v_mov_b32_e32 v89, v79
	v_mul_f32_e32 v90, v65, v79
	v_pk_mul_f32 v[70:71], v[70:71], v[78:79]
	v_pk_mul_f32 v[38:39], v[38:39], v[74:75] op_sel_hi:[1,0]
	v_pk_mul_f32 v[40:41], v[40:41], v[78:79] op_sel:[0,1]
	v_pk_mul_f32 v[54:55], v[54:55], v[74:75] op_sel_hi:[1,0]
	v_pk_mul_f32 v[56:57], v[56:57], v[78:79] op_sel:[0,1]
	v_pk_mul_f32 v[42:43], v[42:43], v[80:81] op_sel_hi:[1,0]
	v_mov_b32_e32 v92, v85
	v_pk_mul_f32 v[44:45], v[44:45], v[80:81] op_sel:[0,1]
	v_pk_mul_f32 v[58:59], v[58:59], v[80:81] op_sel_hi:[1,0]
	v_pk_mul_f32 v[60:61], v[60:61], v[80:81] op_sel:[0,1]
	v_mov_b32_e32 v94, v84
	v_mov_b32_e32 v95, v80
	v_mul_f32_e32 v96, v67, v80
	v_pk_mul_f32 v[76:77], v[76:77], v[80:81]
	v_pk_fma_f32 v[62:63], v[62:63], v[86:87], v[2:3] op_sel_hi:[1,1,0]
	v_pk_fma_f32 v[64:65], v[64:65], v[88:89], v[90:91] op_sel_hi:[1,1,0]
	v_pk_fma_f32 v[70:71], v[82:83], v[74:75], v[70:71]
	v_pk_fma_f32 v[38:39], v[72:73], v[78:79], v[38:39] op_sel_hi:[1,0,1]
	v_pk_fma_f32 v[30:31], v[30:31], v[74:75], v[40:41] op_sel:[0,1,0]
	v_pk_fma_f32 v[36:37], v[36:37], v[78:79], v[54:55] op_sel_hi:[1,0,1]
	v_pk_fma_f32 v[40:41], v[46:47], v[74:75], v[56:57] op_sel:[0,1,0]
	v_mov_b32_e32 v98, v85
	v_mov_b32_e32 v99, v81
	v_mul_f32_e32 v100, v69, v81
	v_pk_fma_f32 v[32:33], v[32:33], v[84:85], v[42:43] op_sel_hi:[1,0,1]
	v_pk_fma_f32 v[34:35], v[34:35], v[92:93], v[44:45] op_sel_hi:[1,0,1]
	v_pk_fma_f32 v[42:43], v[48:49], v[84:85], v[58:59] op_sel_hi:[1,0,1]
	v_pk_fma_f32 v[44:45], v[50:51], v[92:93], v[60:61] op_sel_hi:[1,0,1]
	v_pk_fma_f32 v[46:47], v[66:67], v[94:95], v[96:97] op_sel_hi:[1,1,0]
	v_pk_fma_f32 v[50:51], v[52:53], v[84:85], v[76:77]
	v_pk_add_f32 v[30:31], v[38:39], v[30:31]
	v_pk_add_f32 v[36:37], v[36:37], v[40:41]
	v_mov_b32_e32 v63, v70
	v_mov_b32_e32 v65, v71
	v_pk_fma_f32 v[48:49], v[68:69], v[98:99], v[100:101] op_sel_hi:[1,1,0]
	v_mov_b32_e32 v47, v50
	v_pk_add_f32 v[30:31], v[30:31], v[32:33]
	v_pk_add_f32 v[32:33], v[36:37], v[42:43]
	v_pk_add_f32 v[36:37], v[62:63], v[64:65]
	v_mov_b32_e32 v49, v51
	v_pk_add_f32 v[30:31], v[34:35], v[30:31]
	v_pk_add_f32 v[34:35], v[36:37], v[46:47]
	v_pk_add_f32 v[32:33], v[44:45], v[32:33]
	v_pk_add_f32 v[18:19], v[18:19], v[30:31]
	v_pk_add_f32 v[30:31], v[48:49], v[34:35]
	v_pk_add_f32 v[16:17], v[16:17], v[32:33]
	v_pk_add_f32 v[14:15], v[14:15], v[30:31]
	s_cbranch_scc0 .Lp2_loop
	ds_read_b128 v[30:33], v29
	ds_read_b128 v[34:37], v29 offset:16
	ds_read_b128 v[38:41], v29 offset:8320
	ds_read_b128 v[42:45], v29 offset:8336
	ds_read_b128 v[46:49], v29 offset:16640
	ds_read_b128 v[50:53], v29 offset:16656
	ds_read_b128 v[54:57], v29 offset:24960
	ds_read_b128 v[58:61], v29 offset:24976
	ds_read_b128 v[62:65], v29 offset:33280
	ds_read_b128 v[66:69], v29 offset:33296
	ds_read_b128 v[70:73], v29 offset:41600
	ds_read_b128 v[74:77], v29 offset:41616
	s_add_i32 s10, s10, 1
	s_add_i32 s33, s33, 16
	s_waitcnt lgkmcnt(1)
	v_mov_b32_e32 v82, v71
	v_mov_b32_e32 v83, v72
	v_mov_b32_e32 v71, v73
	v_mov_b32_e32 v72, v30
	v_mov_b32_e32 v73, v38
	v_mov_b32_e32 v38, v31
	v_mov_b32_e32 v30, v32
	v_mov_b32_e32 v31, v40
	v_mov_b32_e32 v40, v33
	v_mov_b32_e32 v32, v34
	v_mov_b32_e32 v33, v42
	v_mov_b32_e32 v42, v35
	v_mov_b32_e32 v34, v36
	v_mov_b32_e32 v35, v44
	v_mov_b32_e32 v44, v37
	v_mov_b32_e32 v36, v46
	v_mov_b32_e32 v37, v54
	v_mov_b32_e32 v54, v47
	v_mov_b32_e32 v46, v48
	v_mov_b32_e32 v47, v56
	v_mov_b32_e32 v56, v49
	v_mov_b32_e32 v48, v50
	v_mov_b32_e32 v49, v58
	v_mov_b32_e32 v58, v51
	v_mov_b32_e32 v50, v52
	v_mov_b32_e32 v51, v60
	v_mov_b32_e32 v60, v53
	s_waitcnt lgkmcnt(0)
	v_mov_b32_e32 v52, v74
	v_mov_b32_e32 v53, v76
	v_mov_b32_e32 v76, v75
	v_add_u32_e32 v29, 32, v29
	v_add_u32_e32 v13, 8, v13
	s_waitcnt vmcnt(3)
	v_and_b32_e32 v74, 0xffff0000, v200
	v_lshlrev_b32_e32 v75, 16, v201
	v_lshlrev_b32_e32 v78, 16, v200
	v_and_b32_e32 v79, 0xffff0000, v201
	v_lshlrev_b32_e32 v85, 16, v203
	v_lshlrev_b32_e32 v84, 16, v202
	v_and_b32_e32 v81, 0xffff0000, v203
	v_and_b32_e32 v80, 0xffff0000, v202
	v_mov_b32_e32 v86, v78
	v_mov_b32_e32 v87, v74
	v_mul_f32_e32 v2, v63, v74
	v_mov_b32_e32 v88, v75
	v_mov_b32_e32 v89, v79
	v_mul_f32_e32 v90, v65, v79
	v_pk_mul_f32 v[70:71], v[70:71], v[78:79]
	v_pk_mul_f32 v[38:39], v[38:39], v[74:75] op_sel_hi:[1,0]
	v_pk_mul_f32 v[40:41], v[40:41], v[78:79] op_sel:[0,1]
	v_pk_mul_f32 v[54:55], v[54:55], v[74:75] op_sel_hi:[1,0]
	v_pk_mul_f32 v[56:57], v[56:57], v[78:79] op_sel:[0,1]
	v_pk_mul_f32 v[42:43], v[42:43], v[80:81] op_sel_hi:[1,0]
	v_mov_b32_e32 v92, v85
	v_pk_mul_f32 v[44:45], v[44:45], v[80:81] op_sel:[0,1]
	v_pk_mul_f32 v[58:59], v[58:59], v[80:81] op_sel_hi:[1,0]
	v_pk_mul_f32 v[60:61], v[60:61], v[80:81] op_sel:[0,1]
	v_mov_b32_e32 v94, v84
	v_mov_b32_e32 v95, v80
	v_mul_f32_e32 v96, v67, v80
	v_pk_mul_f32 v[76:77], v[76:77], v[80:81]
	v_pk_fma_f32 v[62:63], v[62:63], v[86:87], v[2:3] op_sel_hi:[1,1,0]
	v_pk_fma_f32 v[64:65], v[64:65], v[88:89], v[90:91] op_sel_hi:[1,1,0]
	v_pk_fma_f32 v[70:71], v[82:83], v[74:75], v[70:71]
	v_pk_fma_f32 v[38:39], v[72:73], v[78:79], v[38:39] op_sel_hi:[1,0,1]
	v_pk_fma_f32 v[30:31], v[30:31], v[74:75], v[40:41] op_sel:[0,1,0]
	v_pk_fma_f32 v[36:37], v[36:37], v[78:79], v[54:55] op_sel_hi:[1,0,1]
	v_pk_fma_f32 v[40:41], v[46:47], v[74:75], v[56:57] op_sel:[0,1,0]
	v_mov_b32_e32 v98, v85
	v_mov_b32_e32 v99, v81
	v_mul_f32_e32 v100, v69, v81
	v_pk_fma_f32 v[32:33], v[32:33], v[84:85], v[42:43] op_sel_hi:[1,0,1]
	v_pk_fma_f32 v[34:35], v[34:35], v[92:93], v[44:45] op_sel_hi:[1,0,1]
	v_pk_fma_f32 v[42:43], v[48:49], v[84:85], v[58:59] op_sel_hi:[1,0,1]
	v_pk_fma_f32 v[44:45], v[50:51], v[92:93], v[60:61] op_sel_hi:[1,0,1]
	v_pk_fma_f32 v[46:47], v[66:67], v[94:95], v[96:97] op_sel_hi:[1,1,0]
	v_pk_fma_f32 v[50:51], v[52:53], v[84:85], v[76:77]
	v_pk_add_f32 v[30:31], v[38:39], v[30:31]
	v_pk_add_f32 v[36:37], v[36:37], v[40:41]
	v_mov_b32_e32 v63, v70
	v_mov_b32_e32 v65, v71
	v_pk_fma_f32 v[48:49], v[68:69], v[98:99], v[100:101] op_sel_hi:[1,1,0]
	v_mov_b32_e32 v47, v50
	v_pk_add_f32 v[30:31], v[30:31], v[32:33]
	v_pk_add_f32 v[32:33], v[36:37], v[42:43]
	v_pk_add_f32 v[36:37], v[62:63], v[64:65]
	v_mov_b32_e32 v49, v51
	v_pk_add_f32 v[30:31], v[34:35], v[30:31]
	v_pk_add_f32 v[34:35], v[36:37], v[46:47]
	v_pk_add_f32 v[32:33], v[44:45], v[32:33]
	v_pk_add_f32 v[18:19], v[18:19], v[30:31]
	v_pk_add_f32 v[30:31], v[48:49], v[34:35]
	v_pk_add_f32 v[16:17], v[16:17], v[32:33]
	v_pk_add_f32 v[14:15], v[14:15], v[30:31]
	ds_read_b128 v[30:33], v29
	ds_read_b128 v[34:37], v29 offset:16
	ds_read_b128 v[38:41], v29 offset:8320
	ds_read_b128 v[42:45], v29 offset:8336
	ds_read_b128 v[46:49], v29 offset:16640
	ds_read_b128 v[50:53], v29 offset:16656
	ds_read_b128 v[54:57], v29 offset:24960
	ds_read_b128 v[58:61], v29 offset:24976
	ds_read_b128 v[62:65], v29 offset:33280
	ds_read_b128 v[66:69], v29 offset:33296
	ds_read_b128 v[70:73], v29 offset:41600
	ds_read_b128 v[74:77], v29 offset:41616
	s_add_i32 s10, s10, 1
	s_add_i32 s33, s33, 16
	s_waitcnt lgkmcnt(1)
	v_mov_b32_e32 v82, v71
	v_mov_b32_e32 v83, v72
	v_mov_b32_e32 v71, v73
	v_mov_b32_e32 v72, v30
	v_mov_b32_e32 v73, v38
	v_mov_b32_e32 v38, v31
	v_mov_b32_e32 v30, v32
	v_mov_b32_e32 v31, v40
	v_mov_b32_e32 v40, v33
	v_mov_b32_e32 v32, v34
	v_mov_b32_e32 v33, v42
	v_mov_b32_e32 v42, v35
	v_mov_b32_e32 v34, v36
	v_mov_b32_e32 v35, v44
	v_mov_b32_e32 v44, v37
	v_mov_b32_e32 v36, v46
	v_mov_b32_e32 v37, v54
	v_mov_b32_e32 v54, v47
	v_mov_b32_e32 v46, v48
	v_mov_b32_e32 v47, v56
	v_mov_b32_e32 v56, v49
	v_mov_b32_e32 v48, v50
	v_mov_b32_e32 v49, v58
	v_mov_b32_e32 v58, v51
	v_mov_b32_e32 v50, v52
	v_mov_b32_e32 v51, v60
	v_mov_b32_e32 v60, v53
	s_waitcnt lgkmcnt(0)
	v_mov_b32_e32 v52, v74
	v_mov_b32_e32 v53, v76
	v_mov_b32_e32 v76, v75
	v_add_u32_e32 v29, 32, v29
	v_add_u32_e32 v13, 8, v13
	s_waitcnt vmcnt(2)
	v_and_b32_e32 v74, 0xffff0000, v204
	v_lshlrev_b32_e32 v75, 16, v205
	v_lshlrev_b32_e32 v78, 16, v204
	v_and_b32_e32 v79, 0xffff0000, v205
	v_lshlrev_b32_e32 v85, 16, v207
	v_lshlrev_b32_e32 v84, 16, v206
	v_and_b32_e32 v81, 0xffff0000, v207
	v_and_b32_e32 v80, 0xffff0000, v206
	v_mov_b32_e32 v86, v78
	v_mov_b32_e32 v87, v74
	v_mul_f32_e32 v2, v63, v74
	v_mov_b32_e32 v88, v75
	v_mov_b32_e32 v89, v79
	v_mul_f32_e32 v90, v65, v79
	v_pk_mul_f32 v[70:71], v[70:71], v[78:79]
	v_pk_mul_f32 v[38:39], v[38:39], v[74:75] op_sel_hi:[1,0]
	v_pk_mul_f32 v[40:41], v[40:41], v[78:79] op_sel:[0,1]
	v_pk_mul_f32 v[54:55], v[54:55], v[74:75] op_sel_hi:[1,0]
	v_pk_mul_f32 v[56:57], v[56:57], v[78:79] op_sel:[0,1]
	v_pk_mul_f32 v[42:43], v[42:43], v[80:81] op_sel_hi:[1,0]
	v_mov_b32_e32 v92, v85
	v_pk_mul_f32 v[44:45], v[44:45], v[80:81] op_sel:[0,1]
	v_pk_mul_f32 v[58:59], v[58:59], v[80:81] op_sel_hi:[1,0]
	v_pk_mul_f32 v[60:61], v[60:61], v[80:81] op_sel:[0,1]
	v_mov_b32_e32 v94, v84
	v_mov_b32_e32 v95, v80
	v_mul_f32_e32 v96, v67, v80
	v_pk_mul_f32 v[76:77], v[76:77], v[80:81]
	v_pk_fma_f32 v[62:63], v[62:63], v[86:87], v[2:3] op_sel_hi:[1,1,0]
	v_pk_fma_f32 v[64:65], v[64:65], v[88:89], v[90:91] op_sel_hi:[1,1,0]
	v_pk_fma_f32 v[70:71], v[82:83], v[74:75], v[70:71]
	v_pk_fma_f32 v[38:39], v[72:73], v[78:79], v[38:39] op_sel_hi:[1,0,1]
	v_pk_fma_f32 v[30:31], v[30:31], v[74:75], v[40:41] op_sel:[0,1,0]
	v_pk_fma_f32 v[36:37], v[36:37], v[78:79], v[54:55] op_sel_hi:[1,0,1]
	v_pk_fma_f32 v[40:41], v[46:47], v[74:75], v[56:57] op_sel:[0,1,0]
	v_mov_b32_e32 v98, v85
	v_mov_b32_e32 v99, v81
	v_mul_f32_e32 v100, v69, v81
	v_pk_fma_f32 v[32:33], v[32:33], v[84:85], v[42:43] op_sel_hi:[1,0,1]
	v_pk_fma_f32 v[34:35], v[34:35], v[92:93], v[44:45] op_sel_hi:[1,0,1]
	v_pk_fma_f32 v[42:43], v[48:49], v[84:85], v[58:59] op_sel_hi:[1,0,1]
	v_pk_fma_f32 v[44:45], v[50:51], v[92:93], v[60:61] op_sel_hi:[1,0,1]
	v_pk_fma_f32 v[46:47], v[66:67], v[94:95], v[96:97] op_sel_hi:[1,1,0]
	v_pk_fma_f32 v[50:51], v[52:53], v[84:85], v[76:77]
	v_pk_add_f32 v[30:31], v[38:39], v[30:31]
	v_pk_add_f32 v[36:37], v[36:37], v[40:41]
	v_mov_b32_e32 v63, v70
	v_mov_b32_e32 v65, v71
	v_pk_fma_f32 v[48:49], v[68:69], v[98:99], v[100:101] op_sel_hi:[1,1,0]
	v_mov_b32_e32 v47, v50
	v_pk_add_f32 v[30:31], v[30:31], v[32:33]
	v_pk_add_f32 v[32:33], v[36:37], v[42:43]
	v_pk_add_f32 v[36:37], v[62:63], v[64:65]
	v_mov_b32_e32 v49, v51
	v_pk_add_f32 v[30:31], v[34:35], v[30:31]
	v_pk_add_f32 v[34:35], v[36:37], v[46:47]
	v_pk_add_f32 v[32:33], v[44:45], v[32:33]
	v_pk_add_f32 v[18:19], v[18:19], v[30:31]
	v_pk_add_f32 v[30:31], v[48:49], v[34:35]
	v_pk_add_f32 v[16:17], v[16:17], v[32:33]
	v_pk_add_f32 v[14:15], v[14:15], v[30:31]
	ds_read_b128 v[30:33], v29
	ds_read_b128 v[34:37], v29 offset:16
	ds_read_b128 v[38:41], v29 offset:8320
	ds_read_b128 v[42:45], v29 offset:8336
	ds_read_b128 v[46:49], v29 offset:16640
	ds_read_b128 v[50:53], v29 offset:16656
	ds_read_b128 v[54:57], v29 offset:24960
	ds_read_b128 v[58:61], v29 offset:24976
	ds_read_b128 v[62:65], v29 offset:33280
	ds_read_b128 v[66:69], v29 offset:33296
	ds_read_b128 v[70:73], v29 offset:41600
	ds_read_b128 v[74:77], v29 offset:41616
	s_add_i32 s10, s10, 1
	s_add_i32 s33, s33, 16
	s_waitcnt lgkmcnt(1)
	v_mov_b32_e32 v82, v71
	v_mov_b32_e32 v83, v72
	v_mov_b32_e32 v71, v73
	v_mov_b32_e32 v72, v30
	v_mov_b32_e32 v73, v38
	v_mov_b32_e32 v38, v31
	v_mov_b32_e32 v30, v32
	v_mov_b32_e32 v31, v40
	v_mov_b32_e32 v40, v33
	v_mov_b32_e32 v32, v34
	v_mov_b32_e32 v33, v42
	v_mov_b32_e32 v42, v35
	v_mov_b32_e32 v34, v36
	v_mov_b32_e32 v35, v44
	v_mov_b32_e32 v44, v37
	v_mov_b32_e32 v36, v46
	v_mov_b32_e32 v37, v54
	v_mov_b32_e32 v54, v47
	v_mov_b32_e32 v46, v48
	v_mov_b32_e32 v47, v56
	v_mov_b32_e32 v56, v49
	v_mov_b32_e32 v48, v50
	v_mov_b32_e32 v49, v58
	v_mov_b32_e32 v58, v51
	v_mov_b32_e32 v50, v52
	v_mov_b32_e32 v51, v60
	v_mov_b32_e32 v60, v53
	s_waitcnt lgkmcnt(0)
	v_mov_b32_e32 v52, v74
	v_mov_b32_e32 v53, v76
	v_mov_b32_e32 v76, v75
	v_add_u32_e32 v29, 32, v29
	v_add_u32_e32 v13, 8, v13
	s_waitcnt vmcnt(1)
	v_and_b32_e32 v74, 0xffff0000, v208
	v_lshlrev_b32_e32 v75, 16, v209
	v_lshlrev_b32_e32 v78, 16, v208
	v_and_b32_e32 v79, 0xffff0000, v209
	v_lshlrev_b32_e32 v85, 16, v211
	v_lshlrev_b32_e32 v84, 16, v210
	v_and_b32_e32 v81, 0xffff0000, v211
	v_and_b32_e32 v80, 0xffff0000, v210
	v_mov_b32_e32 v86, v78
	v_mov_b32_e32 v87, v74
	v_mul_f32_e32 v2, v63, v74
	v_mov_b32_e32 v88, v75
	v_mov_b32_e32 v89, v79
	v_mul_f32_e32 v90, v65, v79
	v_pk_mul_f32 v[70:71], v[70:71], v[78:79]
	v_pk_mul_f32 v[38:39], v[38:39], v[74:75] op_sel_hi:[1,0]
	v_pk_mul_f32 v[40:41], v[40:41], v[78:79] op_sel:[0,1]
	v_pk_mul_f32 v[54:55], v[54:55], v[74:75] op_sel_hi:[1,0]
	v_pk_mul_f32 v[56:57], v[56:57], v[78:79] op_sel:[0,1]
	v_pk_mul_f32 v[42:43], v[42:43], v[80:81] op_sel_hi:[1,0]
	v_mov_b32_e32 v92, v85
	v_pk_mul_f32 v[44:45], v[44:45], v[80:81] op_sel:[0,1]
	v_pk_mul_f32 v[58:59], v[58:59], v[80:81] op_sel_hi:[1,0]
	v_pk_mul_f32 v[60:61], v[60:61], v[80:81] op_sel:[0,1]
	v_mov_b32_e32 v94, v84
	v_mov_b32_e32 v95, v80
	v_mul_f32_e32 v96, v67, v80
	v_pk_mul_f32 v[76:77], v[76:77], v[80:81]
	v_pk_fma_f32 v[62:63], v[62:63], v[86:87], v[2:3] op_sel_hi:[1,1,0]
	v_pk_fma_f32 v[64:65], v[64:65], v[88:89], v[90:91] op_sel_hi:[1,1,0]
	v_pk_fma_f32 v[70:71], v[82:83], v[74:75], v[70:71]
	v_pk_fma_f32 v[38:39], v[72:73], v[78:79], v[38:39] op_sel_hi:[1,0,1]
	v_pk_fma_f32 v[30:31], v[30:31], v[74:75], v[40:41] op_sel:[0,1,0]
	v_pk_fma_f32 v[36:37], v[36:37], v[78:79], v[54:55] op_sel_hi:[1,0,1]
	v_pk_fma_f32 v[40:41], v[46:47], v[74:75], v[56:57] op_sel:[0,1,0]
	v_mov_b32_e32 v98, v85
	v_mov_b32_e32 v99, v81
	v_mul_f32_e32 v100, v69, v81
	v_pk_fma_f32 v[32:33], v[32:33], v[84:85], v[42:43] op_sel_hi:[1,0,1]
	v_pk_fma_f32 v[34:35], v[34:35], v[92:93], v[44:45] op_sel_hi:[1,0,1]
	v_pk_fma_f32 v[42:43], v[48:49], v[84:85], v[58:59] op_sel_hi:[1,0,1]
	v_pk_fma_f32 v[44:45], v[50:51], v[92:93], v[60:61] op_sel_hi:[1,0,1]
	v_pk_fma_f32 v[46:47], v[66:67], v[94:95], v[96:97] op_sel_hi:[1,1,0]
	v_pk_fma_f32 v[50:51], v[52:53], v[84:85], v[76:77]
	v_pk_add_f32 v[30:31], v[38:39], v[30:31]
	v_pk_add_f32 v[36:37], v[36:37], v[40:41]
	v_mov_b32_e32 v63, v70
	v_mov_b32_e32 v65, v71
	v_pk_fma_f32 v[48:49], v[68:69], v[98:99], v[100:101] op_sel_hi:[1,1,0]
	v_mov_b32_e32 v47, v50
	v_pk_add_f32 v[30:31], v[30:31], v[32:33]
	v_pk_add_f32 v[32:33], v[36:37], v[42:43]
	v_pk_add_f32 v[36:37], v[62:63], v[64:65]
	v_mov_b32_e32 v49, v51
	v_pk_add_f32 v[30:31], v[34:35], v[30:31]
	v_pk_add_f32 v[34:35], v[36:37], v[46:47]
	v_pk_add_f32 v[32:33], v[44:45], v[32:33]
	v_pk_add_f32 v[18:19], v[18:19], v[30:31]
	v_pk_add_f32 v[30:31], v[48:49], v[34:35]
	v_pk_add_f32 v[16:17], v[16:17], v[32:33]
	v_pk_add_f32 v[14:15], v[14:15], v[30:31]
	ds_read_b128 v[30:33], v29
	ds_read_b128 v[34:37], v29 offset:16
	ds_read_b128 v[38:41], v29 offset:8320
	ds_read_b128 v[42:45], v29 offset:8336
	ds_read_b128 v[46:49], v29 offset:16640
	ds_read_b128 v[50:53], v29 offset:16656
	ds_read_b128 v[54:57], v29 offset:24960
	ds_read_b128 v[58:61], v29 offset:24976
	ds_read_b128 v[62:65], v29 offset:33280
	ds_read_b128 v[66:69], v29 offset:33296
	ds_read_b128 v[70:73], v29 offset:41600
	ds_read_b128 v[74:77], v29 offset:41616
	s_add_i32 s10, s10, 1
	s_add_i32 s33, s33, 16
	s_waitcnt lgkmcnt(1)
	v_mov_b32_e32 v82, v71
	v_mov_b32_e32 v83, v72
	v_mov_b32_e32 v71, v73
	v_mov_b32_e32 v72, v30
	v_mov_b32_e32 v73, v38
	v_mov_b32_e32 v38, v31
	v_mov_b32_e32 v30, v32
	v_mov_b32_e32 v31, v40
	v_mov_b32_e32 v40, v33
	v_mov_b32_e32 v32, v34
	v_mov_b32_e32 v33, v42
	v_mov_b32_e32 v42, v35
	v_mov_b32_e32 v34, v36
	v_mov_b32_e32 v35, v44
	v_mov_b32_e32 v44, v37
	v_mov_b32_e32 v36, v46
	v_mov_b32_e32 v37, v54
	v_mov_b32_e32 v54, v47
	v_mov_b32_e32 v46, v48
	v_mov_b32_e32 v47, v56
	v_mov_b32_e32 v56, v49
	v_mov_b32_e32 v48, v50
	v_mov_b32_e32 v49, v58
	v_mov_b32_e32 v58, v51
	v_mov_b32_e32 v50, v52
	v_mov_b32_e32 v51, v60
	v_mov_b32_e32 v60, v53
	s_waitcnt lgkmcnt(0)
	v_mov_b32_e32 v52, v74
	v_mov_b32_e32 v53, v76
	v_mov_b32_e32 v76, v75
	v_add_u32_e32 v29, 32, v29
	v_add_u32_e32 v13, 8, v13
	s_waitcnt vmcnt(0)
	v_and_b32_e32 v74, 0xffff0000, v212
	v_lshlrev_b32_e32 v75, 16, v213
	v_lshlrev_b32_e32 v78, 16, v212
	v_and_b32_e32 v79, 0xffff0000, v213
	v_lshlrev_b32_e32 v85, 16, v215
	v_lshlrev_b32_e32 v84, 16, v214
	v_and_b32_e32 v81, 0xffff0000, v215
	v_and_b32_e32 v80, 0xffff0000, v214
	v_mov_b32_e32 v86, v78
	v_mov_b32_e32 v87, v74
	v_mul_f32_e32 v2, v63, v74
	v_mov_b32_e32 v88, v75
	v_mov_b32_e32 v89, v79
	v_mul_f32_e32 v90, v65, v79
	v_pk_mul_f32 v[70:71], v[70:71], v[78:79]
	v_pk_mul_f32 v[38:39], v[38:39], v[74:75] op_sel_hi:[1,0]
	v_pk_mul_f32 v[40:41], v[40:41], v[78:79] op_sel:[0,1]
	v_pk_mul_f32 v[54:55], v[54:55], v[74:75] op_sel_hi:[1,0]
	v_pk_mul_f32 v[56:57], v[56:57], v[78:79] op_sel:[0,1]
	v_pk_mul_f32 v[42:43], v[42:43], v[80:81] op_sel_hi:[1,0]
	v_mov_b32_e32 v92, v85
	v_pk_mul_f32 v[44:45], v[44:45], v[80:81] op_sel:[0,1]
	v_pk_mul_f32 v[58:59], v[58:59], v[80:81] op_sel_hi:[1,0]
	v_pk_mul_f32 v[60:61], v[60:61], v[80:81] op_sel:[0,1]
	v_mov_b32_e32 v94, v84
	v_mov_b32_e32 v95, v80
	v_mul_f32_e32 v96, v67, v80
	v_pk_mul_f32 v[76:77], v[76:77], v[80:81]
	v_pk_fma_f32 v[62:63], v[62:63], v[86:87], v[2:3] op_sel_hi:[1,1,0]
	v_pk_fma_f32 v[64:65], v[64:65], v[88:89], v[90:91] op_sel_hi:[1,1,0]
	v_pk_fma_f32 v[70:71], v[82:83], v[74:75], v[70:71]
	v_pk_fma_f32 v[38:39], v[72:73], v[78:79], v[38:39] op_sel_hi:[1,0,1]
	v_pk_fma_f32 v[30:31], v[30:31], v[74:75], v[40:41] op_sel:[0,1,0]
	v_pk_fma_f32 v[36:37], v[36:37], v[78:79], v[54:55] op_sel_hi:[1,0,1]
	v_pk_fma_f32 v[40:41], v[46:47], v[74:75], v[56:57] op_sel:[0,1,0]
	v_mov_b32_e32 v98, v85
	v_mov_b32_e32 v99, v81
	v_mul_f32_e32 v100, v69, v81
	v_pk_fma_f32 v[32:33], v[32:33], v[84:85], v[42:43] op_sel_hi:[1,0,1]
	v_pk_fma_f32 v[34:35], v[34:35], v[92:93], v[44:45] op_sel_hi:[1,0,1]
	v_pk_fma_f32 v[42:43], v[48:49], v[84:85], v[58:59] op_sel_hi:[1,0,1]
	v_pk_fma_f32 v[44:45], v[50:51], v[92:93], v[60:61] op_sel_hi:[1,0,1]
	v_pk_fma_f32 v[46:47], v[66:67], v[94:95], v[96:97] op_sel_hi:[1,1,0]
	v_pk_fma_f32 v[50:51], v[52:53], v[84:85], v[76:77]
	v_pk_add_f32 v[30:31], v[38:39], v[30:31]
	v_pk_add_f32 v[36:37], v[36:37], v[40:41]
	v_mov_b32_e32 v63, v70
	v_mov_b32_e32 v65, v71
	v_pk_fma_f32 v[48:49], v[68:69], v[98:99], v[100:101] op_sel_hi:[1,1,0]
	v_mov_b32_e32 v47, v50
	v_pk_add_f32 v[30:31], v[30:31], v[32:33]
	v_pk_add_f32 v[32:33], v[36:37], v[42:43]
	v_pk_add_f32 v[36:37], v[62:63], v[64:65]
	v_mov_b32_e32 v49, v51
	v_pk_add_f32 v[30:31], v[34:35], v[30:31]
	v_pk_add_f32 v[34:35], v[36:37], v[46:47]
	v_pk_add_f32 v[32:33], v[44:45], v[32:33]
	v_pk_add_f32 v[18:19], v[18:19], v[30:31]
	v_pk_add_f32 v[30:31], v[48:49], v[34:35]
	v_pk_add_f32 v[16:17], v[16:17], v[32:33]
	v_pk_add_f32 v[14:15], v[14:15], v[30:31]
	ds_swizzle_b32 v2, v18 offset:swizzle(SWAP,1)
	v_lshl_add_u64 v[20:21], s[6:7], 2, v[4:5]
	s_mul_i32 s6, s31, 0x25800
	s_waitcnt lgkmcnt(0)
	v_add_f32_e32 v2, v18, v2
	ds_swizzle_b32 v7, v2 offset:swizzle(SWAP,2)
	s_waitcnt lgkmcnt(0)
	v_add_f32_e32 v2, v2, v7
	ds_swizzle_b32 v7, v2 offset:swizzle(SWAP,4)
	s_and_saveexec_b64 s[10:11], s[2:3]
	s_cbranch_execz .LBB0_156
	s_waitcnt lgkmcnt(0)
	v_add_f32_e32 v2, v2, v7
	v_lshl_add_u64 v[30:31], v[20:21], 0, s[6:7]
	global_store_dword v[30:31], v2, off

.LBB0_1002:
	s_waitcnt lgkmcnt(0)
	s_barrier
	v_mfma_f32_16x16x32_bf16 v[126:129], v[146:149], v[186:189], v[126:129]
	v_mfma_f32_16x16x32_bf16 v[122:125], v[154:157], v[186:189], v[122:125]
	v_mfma_f32_16x16x32_bf16 v[110:113], v[146:149], v[178:181], v[110:113]
	v_mfma_f32_16x16x32_bf16 v[106:109], v[154:157], v[178:181], v[106:109]
	v_mfma_f32_16x16x32_bf16 v[94:97], v[146:149], v[170:173], v[94:97]
	v_mfma_f32_16x16x32_bf16 v[90:93], v[154:157], v[170:173], v[90:93]
	v_mfma_f32_16x16x32_bf16 v[78:81], v[146:149], v[162:165], v[78:81]
	v_mfma_f32_16x16x32_bf16 v[74:77], v[154:157], v[162:165], v[74:77]
	v_mfma_f32_16x16x32_bf16 v[126:129], v[150:153], v[190:193], v[126:129]
	v_mfma_f32_16x16x32_bf16 v[122:125], v[158:161], v[190:193], v[122:125]
	v_mfma_f32_16x16x32_bf16 v[110:113], v[150:153], v[182:185], v[110:113]
	v_mfma_f32_16x16x32_bf16 v[106:109], v[158:161], v[182:185], v[106:109]
	v_mfma_f32_16x16x32_bf16 v[94:97], v[150:153], v[174:177], v[94:97]
	v_mfma_f32_16x16x32_bf16 v[90:93], v[158:161], v[174:177], v[90:93]
	v_mfma_f32_16x16x32_bf16 v[78:81], v[150:153], v[166:169], v[78:81]
	v_mfma_f32_16x16x32_bf16 v[74:77], v[158:161], v[166:169], v[74:77]
	v_mfma_f32_16x16x32_bf16 v[118:121], v[130:133], v[186:189], v[118:121]
	v_mfma_f32_16x16x32_bf16 v[114:117], v[138:141], v[186:189], v[114:117]
	v_mfma_f32_16x16x32_bf16 v[102:105], v[130:133], v[178:181], v[102:105]
	v_mfma_f32_16x16x32_bf16 v[98:101], v[138:141], v[178:181], v[98:101]
	v_mfma_f32_16x16x32_bf16 v[86:89], v[130:133], v[170:173], v[86:89]
	v_mfma_f32_16x16x32_bf16 v[82:85], v[138:141], v[170:173], v[82:85]
	v_mfma_f32_16x16x32_bf16 v[70:73], v[130:133], v[162:165], v[70:73]
	v_mfma_f32_16x16x32_bf16 v[66:69], v[138:141], v[162:165], v[66:69]
	v_mfma_f32_16x16x32_bf16 v[118:121], v[134:137], v[190:193], v[118:121]
	v_mfma_f32_16x16x32_bf16 v[114:117], v[142:145], v[190:193], v[114:117]
	v_mfma_f32_16x16x32_bf16 v[102:105], v[134:137], v[182:185], v[102:105]
	v_mfma_f32_16x16x32_bf16 v[98:101], v[142:145], v[182:185], v[98:101]
	v_mfma_f32_16x16x32_bf16 v[86:89], v[134:137], v[174:177], v[86:89]
	v_mfma_f32_16x16x32_bf16 v[82:85], v[142:145], v[174:177], v[82:85]
	v_mfma_f32_16x16x32_bf16 v[70:73], v[134:137], v[166:169], v[70:73]
	v_mfma_f32_16x16x32_bf16 v[66:69], v[142:145], v[166:169], v[66:69]
	s_barrier
	s_cmp_lg_u32 s22, 7
	s_cbranch_scc1 .LBB0_997
	s_cmp_gt_u32 s65, 7
	s_waitcnt vmcnt(6)
	v_cvt_f32_ubyte3_e32 v131, v206
	v_cvt_f32_ubyte2_e32 v130, v206
	v_cvt_f32_ubyte1_e32 v133, v206
	v_cvt_f32_ubyte0_e32 v132, v206
	s_cselect_b64 s[16:17], -1, 0
	v_pk_mul_f32 v[134:135], v[132:133], s[20:21] op_sel_hi:[1,0]
	v_pk_mul_f32 v[136:137], v[130:131], s[20:21] op_sel_hi:[1,0]
	v_cvt_f32_ubyte1_e32 v133, v207
	v_cvt_f32_ubyte0_e32 v132, v207
	v_cvt_f32_ubyte3_e32 v131, v207
	v_cvt_f32_ubyte2_e32 v130, v207
	v_pk_mul_f32 v[130:131], v[130:131], s[20:21] op_sel_hi:[1,0]
	v_pk_mul_f32 v[132:133], v[132:133], s[20:21] op_sel_hi:[1,0]
	v_pk_mul_f32 v[128:129], v[136:137], v[128:129]
	v_pk_mul_f32 v[126:127], v[134:135], v[126:127]
	s_mov_b64 s[22:23], -1
	s_and_b64 vcc, exec, s[16:17]
	s_cbranch_vccz .LBB0_1005
	v_pk_add_f32 v[64:65], v[64:65], v[128:129]
	v_pk_add_f32 v[62:63], v[62:63], v[126:127]
	v_pk_fma_f32 v[60:61], v[130:131], v[124:125], v[60:61]
	v_pk_fma_f32 v[58:59], v[132:133], v[122:123], v[58:59]
	s_mov_b64 s[22:23], 0
